# grid barrier: acquire-side buffer_inv issued before the spin (followers) and right after the release writeback (XCD leader) instead of after release detection
# speedup vs baseline: 1.0316x; 1.0316x over previous
.LBB0_527:
	s_or_b64 exec, exec, s[2:3]
	v_cvt_f32_u32_e32 v4, v2
	s_waitcnt vmcnt(0)
	v_readfirstlane_b32 s2, v3
	v_sub_u32_e32 v3, 0, v2
	v_rcp_iflag_f32_e32 v4, v4
	v_add_u32_e32 v5, s2, v1
	v_mul_f32_e32 v4, 0x4f7ffffe, v4
	v_cvt_u32_f32_e32 v4, v4
	v_mul_lo_u32 v1, v3, v4
	v_mul_hi_u32 v1, v4, v1
	v_add_u32_e32 v1, v4, v1
	v_mul_hi_u32 v1, v5, v1
	v_mul_lo_u32 v3, v1, v2
	v_sub_u32_e32 v3, v5, v3
	v_add_u32_e32 v4, 1, v1
	v_cmp_ge_u32_e32 vcc, v3, v2
	s_nop 1
	v_cndmask_b32_e32 v1, v1, v4, vcc
	v_sub_u32_e32 v4, v3, v2
	v_cndmask_b32_e32 v3, v3, v4, vcc
	v_add_u32_e32 v4, 1, v1
	v_cmp_ge_u32_e32 vcc, v3, v2
	v_add_u32_e32 v3, 1, v5
	s_nop 0
	v_cndmask_b32_e32 v1, v1, v4, vcc
	v_mul_lo_u32 v4, v2, v1
	v_add_u32_e32 v2, v4, v2
	v_cmp_ne_u32_e32 vcc, v3, v2
	s_and_saveexec_b64 s[2:3], vcc
	s_xor_b64 s[2:3], exec, s[2:3]
	s_cbranch_execz .LBB0_541
	v_readlane_b32 s8, v254, 40
	v_readlane_b32 s9, v254, 41
	s_waitcnt lgkmcnt(0)
	s_nop 3
	buffer_inv sc1
	global_load_dword v0, v117, s[8:9] sc1
	s_waitcnt vmcnt(0)
	v_cmp_eq_u32_e32 vcc, v0, v1
	s_and_saveexec_b64 s[8:9], vcc
	s_cbranch_execz .LBB0_540
	s_mov_b32 s20, 1
	s_mov_b64 s[10:11], 0
	s_branch .LBB0_531

.LBB0_540:
	s_or_b64 exec, exec, s[8:9]
	s_waitcnt vmcnt(0)
	s_waitcnt vmcnt(0)

.LBB0_542:
	s_mov_b64 s[2:3], exec
	buffer_wbl2 sc1
	s_waitcnt lgkmcnt(0)
	s_waitcnt vmcnt(0)
	buffer_inv sc1
	v_mbcnt_lo_u32_b32 v1, s2, 0
	v_mbcnt_hi_u32_b32 v1, s3, v1
	v_cmp_eq_u32_e32 vcc, 0, v1
	s_and_saveexec_b64 s[8:9], vcc
	s_cbranch_execz .LBB0_544
	s_bcnt1_i32_b64 s2, s[2:3]
	v_mov_b32_e32 v2, s2
	v_readlane_b32 s2, v254, 42
	v_readlane_b32 s3, v254, 43
	s_nop 4
	global_atomic_add v2, v117, v2, s[2:3] sc0

.LBB0_558:
	s_or_b64 exec, exec, s[2:3]
	s_mov_b64 s[2:3], exec
	v_mbcnt_lo_u32_b32 v0, s2, 0
	v_mbcnt_hi_u32_b32 v0, s3, v0
	v_cmp_eq_u32_e32 vcc, 0, v0
	s_waitcnt vmcnt(0)
	s_and_saveexec_b64 s[8:9], vcc
	s_cbranch_execnz .LBB0_559
	s_getpc_b64 s[98:99]
